# deferred weight conversion: last 5376 tiles of the w_down f32->bf16 transpose moved out of phase 0 into the 42 workgroups idle in the last round of the gate-up GEMM phase
# speedup vs baseline: 1.0068x; 1.0034x over previous
.LBB0_7:
	s_or_b64 exec, exec, s[4:5]
	s_lshl_b32 s18, s30, 3
	s_add_u32 s68, s28, 0x400000
	s_addc_u32 s69, s29, 0
	s_add_u32 s14, s28, 0x13000000
	s_addc_u32 s15, s29, 0
	s_add_u32 s10, s28, 0x17000000
	s_load_dwordx16 s[52:67], s[0:1], 0x0
	s_load_dwordx16 s[36:51], s[0:1], 0x40
	s_addc_u32 s11, s29, 0
	v_mov_b32_e32 v94, v226
	s_add_u32 s12, s28, 0x19000000
	s_addc_u32 s13, s29, 0
	v_readfirstlane_b32 s0, v94
	s_ashr_i32 s78, s0, 6
	s_lshl_b32 s0, s89, 3
	v_and_b32_e32 v1, 63, v94
	s_add_i32 s79, s78, s0
	s_cmp_gt_i32 s79, 0xb1ff
	v_lshlrev_b32_e32 v66, 4, v1
	v_writelane_b32 v254, s0, 3
	v_writelane_b32 v254, s22, 10
	v_writelane_b32 v254, s23, 11
	s_cbranch_scc1 .LBB0_34
	v_lshlrev_b32_e32 v3, 6, v1
	v_lshlrev_b32_e32 v2, 2, v1
	v_and_b32_e32 v70, 0x180, v3
	v_and_b32_e32 v3, 7, v94
	v_and_b32_e32 v71, 28, v2
	v_and_b32_e32 v2, 24, v94
	v_mov_b32_e32 v69, 0
	v_lshlrev_b32_e32 v68, 1, v70
	v_lshlrev_b32_e32 v3, 4, v3
	v_lshl_add_u64 v[72:73], s[12:13], 0, v[68:69]
	v_lshlrev_b32_e32 v4, 1, v2
	v_mov_b32_e32 v5, v69
	v_lshl_add_u64 v[76:77], s[26:27], 0, v[68:69]
	s_waitcnt lgkmcnt(0)
	s_cmp_lg_u64 s[44:45], 0
	v_lshl_add_u64 v[80:81], s[10:11], 0, v[68:69]
	v_lshl_or_b32 v85, s79, 8, v3
	v_lshlrev_b32_e32 v3, 2, v71
	v_and_b32_e32 v67, 56, v94
	v_lshl_add_u64 v[74:75], v[72:73], 0, v[4:5]
	v_and_b32_e32 v84, 16, v66
	v_lshl_add_u64 v[78:79], v[76:77], 0, v[4:5]
	s_cselect_b64 s[0:1], -1, 0
	v_lshl_add_u64 v[82:83], v[80:81], 0, v[4:5]
	s_lshl_b32 s19, s79, 6
	s_lshl_b32 s80, s18, 6
	s_lshl_b32 s81, s18, 8
	s_lshl_b32 s82, s79, 3
	s_lshl_b32 s83, s18, 3
	s_mov_b32 s5, 0
	s_mov_b64 s[6:7], 0x80
	v_and_b32_e32 v86, 16, v3
	s_mov_b64 s[8:9], 0xc0
	s_mov_b32 s84, 0xa000
	s_mov_b32 s85, 0x15000
	s_mov_b32 s86, 0x20000
	s_mov_b32 s87, 0x2b000
	s_mov_b32 s88, 0x35000
	s_mov_b32 s90, 0x40000
	s_mov_b32 s91, 0x100000
	s_mov_b32 s93, 0x140000
	s_mov_b64 s[72:73], 0x1400c0
	s_mov_b64 s[74:75], 0x400c0
	v_lshlrev_b32_e32 v68, 1, v2
	v_mov_b32_e32 v87, 0x40000
	s_mov_b32 s94, s79
	s_branch .LBB0_10
.LBB0_9:
	s_add_i32 s94, s94, s18
	s_add_i32 s19, s19, s80
	s_add_i32 s82, s82, s83
	s_cmp_lt_u32 s94, 0x9c00
	s_cbranch_scc1 .Ldf_nohole
	s_cmp_gt_u32 s94, 0xb0ff
	s_cbranch_scc1 .Ldf_nohole
	s_add_i32 s94, s94, 0x1500
	s_add_i32 s19, s19, 0x54000
	s_add_i32 s82, s82, 0xa800
	v_add_u32_e32 v85, 0x150000, v85
.Ldf_nohole:
	v_lshl_add_u64 v[6:7], v[6:7], 0, v[68:69]
	s_cmp_gt_i32 s94, 0xb1ff
	v_add_u32_e32 v85, s81, v85
	global_store_dwordx4 v[6:7], v[2:5], off
	s_cbranch_scc1 .LBB0_34

.LBB0_695:
	v_readfirstlane_b32 s96, v226
	s_lshr_b32 s96, s96, 6
	s_cmp_eq_u32 s78, 0x100
	s_cbranch_scc1 .Ldf_g256
	s_lshl_b32 s97, s2, 3
	s_lshl_b32 s93, s78, 3
	s_branch .Ldf_go
.Ldf_g256:
	s_cmp_lt_u32 s2, 214
	s_cbranch_scc1 .Ldf_done
	s_sub_i32 s97, s2, 214
	s_lshl_b32 s97, s97, 3
	s_movk_i32 s93, 336
.Ldf_go:
	s_add_i32 s97, s97, s96
	s_add_i32 s94, s97, 0x9c00
	v_readlane_b32 s98, v254, 10
	v_readlane_b32 s99, v254, 11
	s_mov_b64 s[80:81], 0x80
	s_mov_b64 s[82:83], 0xc0
	v_and_b32_e32 v1, 63, v226
	v_lshlrev_b32_e32 v66, 4, v1
	v_lshlrev_b32_e32 v3, 6, v1
	v_and_b32_e32 v70, 0x180, v3
	v_lshlrev_b32_e32 v2, 2, v1
	v_and_b32_e32 v71, 28, v2
	v_and_b32_e32 v2, 24, v226
	v_mov_b32_e32 v69, 0
	v_lshlrev_b32_e32 v68, 1, v70
	v_lshl_add_u64 v[76:77], s[26:27], 0, v[68:69]
	v_lshlrev_b32_e32 v4, 1, v2
	v_mov_b32_e32 v5, v69
	v_lshl_add_u64 v[78:79], v[76:77], 0, v[4:5]
	v_and_b32_e32 v67, 56, v226
	v_and_b32_e32 v84, 16, v66
	v_lshlrev_b32_e32 v68, 1, v2
.Ldf_loop:
	s_lshl_b32 s95, s94, 6
	s_add_i32 s96, s94, 0x7a00
	s_and_b32 s96, s96, 0xffc0
	v_or_b32_e32 v88, s96, v67
	s_and_b32 s96, s95, 0xfc0
	v_or_b32_e32 v2, s96, v71
	v_lshlrev_b32_e32 v2, 2, v2
	v_mov_b32_e32 v3, v69
	v_lshlrev_b32_e32 v30, 14, v88
	v_lshl_add_u64 v[34:35], s[98:99], 0, v[2:3]
	v_mov_b32_e32 v31, v69
	v_or_b32_e32 v38, 0x4000, v30
	v_mov_b32_e32 v39, v69
	v_or_b32_e32 v42, 0x8000, v30
	v_mov_b32_e32 v43, v69
	v_or_b32_e32 v44, 0xc000, v30
	v_mov_b32_e32 v45, v69
	v_or_b32_e32 v50, 0x10000, v30
	v_mov_b32_e32 v51, v69
	v_or_b32_e32 v52, 0x14000, v30
	v_mov_b32_e32 v53, v69
	v_or_b32_e32 v58, 0x18000, v30
	v_mov_b32_e32 v59, v69
	v_lshl_add_u64 v[36:37], v[34:35], 0, v[30:31]
	v_lshl_add_u64 v[6:7], v[34:35], 0, v[38:39]
	v_lshl_add_u64 v[10:11], v[34:35], 0, v[42:43]
	v_lshl_add_u64 v[14:15], v[34:35], 0, v[44:45]
	v_lshl_add_u64 v[18:19], v[34:35], 0, v[50:51]
	v_lshl_add_u64 v[22:23], v[34:35], 0, v[52:53]
	v_lshl_add_u64 v[26:27], v[34:35], 0, v[58:59]
	global_load_dwordx4 v[2:5], v[36:37], off
	s_nop 0
	global_load_dwordx4 v[6:9], v[6:7], off
	s_nop 0
	global_load_dwordx4 v[10:13], v[10:11], off
	s_nop 0
	global_load_dwordx4 v[14:17], v[14:15], off
	s_nop 0
	global_load_dwordx4 v[18:21], v[18:19], off
	s_nop 0
	global_load_dwordx4 v[22:25], v[22:23], off
	s_nop 0
	global_load_dwordx4 v[26:29], v[26:27], off
	v_or_b32_e32 v60, 0x1c000, v30
	v_mov_b32_e32 v61, v69
	v_lshl_add_u64 v[62:63], v[34:35], 0, s[80:81]
	v_lshl_add_u64 v[30:31], v[34:35], 0, v[60:61]
	v_lshl_add_u64 v[38:39], v[62:63], 0, v[38:39]
	v_lshl_add_u64 v[42:43], v[62:63], 0, v[42:43]
	v_lshl_add_u64 v[46:47], v[62:63], 0, v[44:45]
	v_lshl_add_u64 v[50:51], v[62:63], 0, v[50:51]
	v_lshl_add_u64 v[54:55], v[62:63], 0, v[52:53]
	v_lshl_add_u64 v[58:59], v[62:63], 0, v[58:59]
	v_lshl_add_u64 v[62:63], v[62:63], 0, v[60:61]
	global_load_dwordx4 v[30:33], v[30:31], off
	v_or_b32_e32 v90, s96, v84
	global_load_dwordx4 v[34:37], v[36:37], off offset:128
	v_lshrrev_b32_e32 v90, 4, v90
	global_load_dwordx4 v[38:41], v[38:39], off
	s_nop 0
	global_load_dwordx4 v[42:45], v[42:43], off
	s_nop 0
	global_load_dwordx4 v[46:49], v[46:47], off
	s_nop 0
	global_load_dwordx4 v[50:53], v[50:51], off
	s_nop 0
	global_load_dwordx4 v[54:57], v[54:55], off
	s_nop 0
	global_load_dwordx4 v[58:61], v[58:59], off
	s_nop 0
	global_load_dwordx4 v[62:65], v[62:63], off
	v_lshrrev_b32_e32 v88, 5, v88
	v_mul_u32_u24_e32 v90, 0x158, v90
	v_mov_b32_e32 v89, v69
	v_add_lshl_u32 v88, v90, v88, 10
	v_lshl_add_u64 v[96:97], v[78:79], 0, v[88:89]
	v_add_u32_e32 v92, 0xac000, v88
	v_mov_b32_e32 v93, v69
	v_lshl_add_u64 v[98:99], v[78:79], 0, v[92:93]
	s_waitcnt vmcnt(14)
	v_cvt_pk_bf16_f32 v88, v2, v6
	s_waitcnt vmcnt(12)
	v_cvt_pk_bf16_f32 v89, v10, v14
	s_waitcnt vmcnt(10)
	v_cvt_pk_bf16_f32 v90, v18, v22
	s_waitcnt vmcnt(8)
	v_cvt_pk_bf16_f32 v91, v26, v30
	global_store_dwordx4 v[96:97], v[88:91], off
	s_nop 1
	v_cvt_pk_bf16_f32 v88, v3, v7
	v_cvt_pk_bf16_f32 v89, v11, v15
	v_cvt_pk_bf16_f32 v90, v19, v23
	v_cvt_pk_bf16_f32 v91, v27, v31
	global_store_dwordx4 v[96:97], v[88:91], off offset:64
	v_lshl_add_u64 v[6:7], v[76:77], 0, v[92:93]
	s_nop 0
	v_cvt_pk_bf16_f32 v88, v4, v8
	v_cvt_pk_bf16_f32 v89, v12, v16
	v_cvt_pk_bf16_f32 v90, v20, v24
	v_cvt_pk_bf16_f32 v91, v28, v32
	global_store_dwordx4 v[96:97], v[88:91], off offset:128
	v_cvt_pk_bf16_f32 v2, v5, v9
	v_cvt_pk_bf16_f32 v3, v13, v17
	v_cvt_pk_bf16_f32 v4, v21, v25
	v_cvt_pk_bf16_f32 v5, v29, v33
	global_store_dwordx4 v[96:97], v[2:5], off offset:192
	v_lshl_add_u64 v[8:9], v[6:7], 0, v[68:69]
	v_lshl_add_u64 v[6:7], v[6:7], 0, s[82:83]
	s_waitcnt vmcnt(10)
	v_cvt_pk_bf16_f32 v2, v34, v38
	s_waitcnt vmcnt(8)
	v_cvt_pk_bf16_f32 v3, v42, v46
	s_waitcnt vmcnt(6)
	v_cvt_pk_bf16_f32 v4, v50, v54
	s_waitcnt vmcnt(4)
	v_cvt_pk_bf16_f32 v5, v58, v62
	global_store_dwordx4 v[98:99], v[2:5], off
	s_nop 1
	v_cvt_pk_bf16_f32 v2, v35, v39
	v_cvt_pk_bf16_f32 v3, v43, v47
	v_cvt_pk_bf16_f32 v4, v51, v55
	v_cvt_pk_bf16_f32 v5, v59, v63
	global_store_dwordx4 v[8:9], v[2:5], off offset:64
	s_nop 1
	v_cvt_pk_bf16_f32 v2, v36, v40
	v_cvt_pk_bf16_f32 v3, v44, v48
	v_cvt_pk_bf16_f32 v4, v52, v56
	v_cvt_pk_bf16_f32 v5, v60, v64
	global_store_dwordx4 v[8:9], v[2:5], off offset:128
	s_nop 1
	v_cvt_pk_bf16_f32 v2, v37, v41
	v_cvt_pk_bf16_f32 v3, v45, v49
	v_cvt_pk_bf16_f32 v4, v53, v57
	v_cvt_pk_bf16_f32 v5, v61, v65
	v_lshl_add_u64 v[6:7], v[6:7], 0, v[68:69]
	global_store_dwordx4 v[6:7], v[2:5], off
	s_add_i32 s94, s94, s93
	s_cmp_gt_u32 s94, 0xb0ff
	s_cbranch_scc0 .Ldf_loop
